# row-op rows mapped to the 8-block group that owns the GEMM row tile; grid barriers on group-local hand-offs skip the L2 write-back when a run-time check finds blocks b and b+8k on one XCD; hand-writte
# speedup vs baseline: 1.0096x; 1.0082x over previous
_Z2mk1Pii:
	s_load_dwordx4 s[44:47], s[0:1], 0x190
	s_add_u32 s4, s0, 0x198
	s_addc_u32 s5, s1, 0
	v_writelane_b32 v164, s2, 0
	v_writelane_b32 v162, 0, 60
	v_writelane_b32 v162, 0, 62
	s_waitcnt lgkmcnt(0)
	s_cmp_lt_i32 s45, 0
	s_cbranch_scc1 .LBB0_2
	v_and_b32_e32 v128, 0x3ff, v0
	s_load_dword s33, s[0:1], 0x1a0
	s_cbranch_execz .LBB0_3
	s_branch .LBB0_14

.LBB0_45:
	s_and_b32 s26, 0xffff, s37
	v_cvt_f32_u32_e32 v0, s26
	s_and_b32 s26, 0xffff, s36
	v_cvt_f32_u32_e32 v1, s26
	v_mov_b32_e32 v8, v128
	v_rcp_iflag_f32_e32 v2, v0
	v_mov_b32_e32 v4, 0
	v_ashrrev_i32_e32 v9, 4, v8
	v_mul_f32_e32 v2, v1, v2
	v_trunc_f32_e32 v2, v2
	v_cvt_u32_f32_e32 v3, v2
	v_fma_f32 v1, -v2, v0, v1
	v_cmp_ge_f32_e64 s[26:27], |v1|, v0
	s_cmp_lg_u64 s[26:27], 0
	v_readfirstlane_b32 s26, v3
	s_addc_u32 s26, s26, 0
	s_and_b32 s27, s26, 0xffff
	s_mul_i32 s35, s26, s37
	s_lshl_b32 s26, s27, 6
	s_sub_i32 s27, s36, s35
	s_lshl_b32 s27, s27, 6
	v_lshlrev_b32_e32 v0, 2, v8
	s_and_b32 s27, s27, 0xffc0
	v_and_b32_e32 v1, 60, v0
	v_or_b32_e32 v0, s27, v1
	v_lshlrev_b32_e32 v12, 2, v0
	v_cmp_gt_u32_e32 vcc, s0, v0
	v_lshl_add_u64 v[6:7], s[24:25], 0, v[12:13]
	v_lshrrev_b32_e32 v36, 4, v128
	v_and_b32_e32 v37, 15, v128
	v_lshlrev_b32_e32 v37, 2, v37
	s_movk_i32 s50, 0x104
	v_mul_lo_u32 v41, v36, s50
	v_lshl_add_u32 v20, v37, 2, v41
	v_add_u32_e32 v21, 0x1040, v20
	v_add_u32_e32 v22, 0x2080, v20
	v_add_u32_e32 v23, 0x30c0, v20
	v_add_u32_e32 v24, 0x4200, v20
	v_add_u32_e32 v25, 0x4200, v21
	v_add_u32_e32 v26, 0x4200, v22
	v_add_u32_e32 v27, 0x4200, v23
	v_and_b32_e32 v41, 3, v128
	v_lshlrev_b32_e32 v41, 3, v41
	v_mul_lo_u32 v28, v41, s50
	v_and_b32_e32 v42, -4, v128
	v_add_u32_e32 v28, v28, v42
	v_add_u32_e32 v29, 0x400, v28
	v_add_u32_e32 v30, 0x2080, v28
	v_add_u32_e32 v31, 0x2480, v28
	v_add_u32_e32 v32, 0x4200, v28
	v_add_u32_e32 v33, 0x4200, v29
	v_add_u32_e32 v34, 0x4200, v30
	v_add_u32_e32 v35, 0x4200, v31
	v_add_u32_e32 v38, s26, v36
	v_mul_lo_u32 v38, v38, s0
	v_lshlrev_b32_e32 v38, 2, v38
	s_lshl_b32 s51, s0, 6
	s_sub_u32 s52, s0, 4
	v_lshrrev_b32_e32 v39, 2, v128
	v_add_u32_e32 v39, s27, v39
	v_mul_lo_u32 v39, v39, s22
	v_add_u32_e32 v39, s26, v39
	v_add_u32_e32 v39, v41, v39
	v_lshlrev_b32_e32 v39, 1, v39
	s_lshl_b32 s53, s22, 7
	v_add_u32_e32 v40, s27, v37
	v_min_u32_e32 v40, s52, v40
	v_lshl_add_u32 v112, v40, 2, v38
	v_add_u32_e32 v113, s51, v112
	v_add_u32_e32 v114, s51, v113
	v_add_u32_e32 v115, s51, v114
	global_load_dwordx4 v[48:51], v112, s[24:25] nt
	global_load_dwordx4 v[52:55], v113, s[24:25] nt
	global_load_dwordx4 v[56:59], v114, s[24:25] nt
	global_load_dwordx4 v[60:63], v115, s[24:25] nt
	v_add_u32_e32 v40, s27, v37
	v_add_u32_e32 v40, 64, v40
	v_min_u32_e32 v40, s52, v40
	v_lshl_add_u32 v112, v40, 2, v38
	v_add_u32_e32 v113, s51, v112
	v_add_u32_e32 v114, s51, v113
	v_add_u32_e32 v115, s51, v114
	global_load_dwordx4 v[64:67], v112, s[24:25] nt
	global_load_dwordx4 v[68:71], v113, s[24:25] nt
	global_load_dwordx4 v[72:75], v114, s[24:25] nt
	global_load_dwordx4 v[76:79], v115, s[24:25] nt
	v_add_u32_e32 v40, s27, v37
	v_add_u32_e32 v40, 128, v40
	v_min_u32_e32 v40, s52, v40
	v_lshl_add_u32 v112, v40, 2, v38
	v_add_u32_e32 v113, s51, v112
	v_add_u32_e32 v114, s51, v113
	v_add_u32_e32 v115, s51, v114
	global_load_dwordx4 v[80:83], v112, s[24:25] nt
	global_load_dwordx4 v[84:87], v113, s[24:25] nt
	global_load_dwordx4 v[88:91], v114, s[24:25] nt
	global_load_dwordx4 v[92:95], v115, s[24:25] nt
	v_add_u32_e32 v40, s27, v37
	v_add_u32_e32 v40, 192, v40
	v_min_u32_e32 v40, s52, v40
	v_lshl_add_u32 v112, v40, 2, v38
	v_add_u32_e32 v113, s51, v112
	v_add_u32_e32 v114, s51, v113
	v_add_u32_e32 v115, s51, v114
	global_load_dwordx4 v[96:99], v112, s[24:25] nt
	global_load_dwordx4 v[100:103], v113, s[24:25] nt
	global_load_dwordx4 v[104:107], v114, s[24:25] nt
	global_load_dwordx4 v[108:111], v115, s[24:25] nt
	v_add_u32_e32 v40, s27, v37
	v_add_u32_e32 v40, 256, v40
	v_min_u32_e32 v40, s52, v40
	v_lshl_add_u32 v112, v40, 2, v38
	v_add_u32_e32 v113, s51, v112
	v_add_u32_e32 v114, s51, v113
	v_add_u32_e32 v115, s51, v114
	global_load_dwordx4 v[168:171], v112, s[24:25] nt
	global_load_dwordx4 v[172:175], v113, s[24:25] nt
	global_load_dwordx4 v[176:179], v114, s[24:25] nt
	global_load_dwordx4 v[180:183], v115, s[24:25] nt
	v_add_u32_e32 v40, s27, v37
	v_add_u32_e32 v40, 320, v40
	v_min_u32_e32 v40, s52, v40
	v_lshl_add_u32 v112, v40, 2, v38
	v_add_u32_e32 v113, s51, v112
	v_add_u32_e32 v114, s51, v113
	v_add_u32_e32 v115, s51, v114
	global_load_dwordx4 v[184:187], v112, s[24:25] nt
	global_load_dwordx4 v[188:191], v113, s[24:25] nt
	global_load_dwordx4 v[192:195], v114, s[24:25] nt
	global_load_dwordx4 v[196:199], v115, s[24:25] nt
	v_add_u32_e32 v40, s27, v37
	v_add_u32_e32 v40, 384, v40
	v_min_u32_e32 v40, s52, v40
	v_lshl_add_u32 v112, v40, 2, v38
	v_add_u32_e32 v113, s51, v112
	v_add_u32_e32 v114, s51, v113
	v_add_u32_e32 v115, s51, v114
	global_load_dwordx4 v[200:203], v112, s[24:25] nt
	global_load_dwordx4 v[204:207], v113, s[24:25] nt
	global_load_dwordx4 v[208:211], v114, s[24:25] nt
	global_load_dwordx4 v[212:215], v115, s[24:25] nt
	v_add_u32_e32 v40, s27, v37
	v_add_u32_e32 v40, 448, v40
	v_min_u32_e32 v40, s52, v40
	v_lshl_add_u32 v112, v40, 2, v38
	v_add_u32_e32 v113, s51, v112
	v_add_u32_e32 v114, s51, v113
	v_add_u32_e32 v115, s51, v114
	global_load_dwordx4 v[216:219], v112, s[24:25] nt
	global_load_dwordx4 v[220:223], v113, s[24:25] nt
	global_load_dwordx4 v[224:227], v114, s[24:25] nt
	global_load_dwordx4 v[228:231], v115, s[24:25] nt
	s_waitcnt vmcnt(28)
	v_add_u32_e32 v40, s27, v37
	v_cmp_gt_u32_e32 vcc, s0, v40
	s_nop 1
	v_cndmask_b32_e32 v48, 0, v48, vcc
	v_cndmask_b32_e32 v49, 0, v49, vcc
	v_cndmask_b32_e32 v50, 0, v50, vcc
	v_cndmask_b32_e32 v51, 0, v51, vcc
	v_cndmask_b32_e32 v52, 0, v52, vcc
	v_cndmask_b32_e32 v53, 0, v53, vcc
	v_cndmask_b32_e32 v54, 0, v54, vcc
	v_cndmask_b32_e32 v55, 0, v55, vcc
	v_cndmask_b32_e32 v56, 0, v56, vcc
	v_cndmask_b32_e32 v57, 0, v57, vcc
	v_cndmask_b32_e32 v58, 0, v58, vcc
	v_cndmask_b32_e32 v59, 0, v59, vcc
	v_cndmask_b32_e32 v60, 0, v60, vcc
	v_cndmask_b32_e32 v61, 0, v61, vcc
	v_cndmask_b32_e32 v62, 0, v62, vcc
	v_cndmask_b32_e32 v63, 0, v63, vcc
	ds_write2_b32 v20, v48, v49 offset1:1
	ds_write2_b32 v20, v50, v51 offset0:2 offset1:3
	ds_write2_b32 v21, v52, v53 offset1:1
	ds_write2_b32 v21, v54, v55 offset0:2 offset1:3
	ds_write2_b32 v22, v56, v57 offset1:1
	ds_write2_b32 v22, v58, v59 offset0:2 offset1:3
	ds_write2_b32 v23, v60, v61 offset1:1
	ds_write2_b32 v23, v62, v63 offset0:2 offset1:3
	s_waitcnt lgkmcnt(0)
	s_barrier
	ds_read2_b32 v[232:233], v28 offset0:0 offset1:65
	ds_read2_b32 v[234:235], v28 offset0:130 offset1:195
	ds_read2_b32 v[236:237], v29 offset0:4 offset1:69
	ds_read2_b32 v[238:239], v29 offset0:134 offset1:199
	ds_read2_b32 v[240:241], v30 offset0:0 offset1:65
	ds_read2_b32 v[242:243], v30 offset0:130 offset1:195
	ds_read2_b32 v[244:245], v31 offset0:4 offset1:69
	ds_read2_b32 v[246:247], v31 offset0:134 offset1:199
	s_waitcnt lgkmcnt(0)
	v_cvt_pk_bf16_f32 v248, v232, v233
	v_cvt_pk_bf16_f32 v249, v234, v235
	v_cvt_pk_bf16_f32 v250, v236, v237
	v_cvt_pk_bf16_f32 v251, v238, v239
	v_cvt_pk_bf16_f32 v252, v240, v241
	v_cvt_pk_bf16_f32 v253, v242, v243
	v_cvt_pk_bf16_f32 v254, v244, v245
	v_cvt_pk_bf16_f32 v255, v246, v247
	global_store_dwordx4 v39, v[248:251], s[20:21]
	global_store_dwordx4 v39, v[252:255], s[20:21] offset:64
	v_add_u32_e32 v39, s53, v39
	s_waitcnt vmcnt(26)
	v_add_u32_e32 v40, s27, v37
	v_add_u32_e32 v40, 64, v40
	v_cmp_gt_u32_e32 vcc, s0, v40
	s_nop 1
	v_cndmask_b32_e32 v64, 0, v64, vcc
	v_cndmask_b32_e32 v65, 0, v65, vcc
	v_cndmask_b32_e32 v66, 0, v66, vcc
	v_cndmask_b32_e32 v67, 0, v67, vcc
	v_cndmask_b32_e32 v68, 0, v68, vcc
	v_cndmask_b32_e32 v69, 0, v69, vcc
	v_cndmask_b32_e32 v70, 0, v70, vcc
	v_cndmask_b32_e32 v71, 0, v71, vcc
	v_cndmask_b32_e32 v72, 0, v72, vcc
	v_cndmask_b32_e32 v73, 0, v73, vcc
	v_cndmask_b32_e32 v74, 0, v74, vcc
	v_cndmask_b32_e32 v75, 0, v75, vcc
	v_cndmask_b32_e32 v76, 0, v76, vcc
	v_cndmask_b32_e32 v77, 0, v77, vcc
	v_cndmask_b32_e32 v78, 0, v78, vcc
	v_cndmask_b32_e32 v79, 0, v79, vcc
	ds_write2_b32 v24, v64, v65 offset1:1
	ds_write2_b32 v24, v66, v67 offset0:2 offset1:3
	ds_write2_b32 v25, v68, v69 offset1:1
	ds_write2_b32 v25, v70, v71 offset0:2 offset1:3
	ds_write2_b32 v26, v72, v73 offset1:1
	ds_write2_b32 v26, v74, v75 offset0:2 offset1:3
	ds_write2_b32 v27, v76, v77 offset1:1
	ds_write2_b32 v27, v78, v79 offset0:2 offset1:3
	s_waitcnt lgkmcnt(0)
	s_barrier
	ds_read2_b32 v[232:233], v32 offset0:0 offset1:65
	ds_read2_b32 v[234:235], v32 offset0:130 offset1:195
	ds_read2_b32 v[236:237], v33 offset0:4 offset1:69
	ds_read2_b32 v[238:239], v33 offset0:134 offset1:199
	ds_read2_b32 v[240:241], v34 offset0:0 offset1:65
	ds_read2_b32 v[242:243], v34 offset0:130 offset1:195
	ds_read2_b32 v[244:245], v35 offset0:4 offset1:69
	ds_read2_b32 v[246:247], v35 offset0:134 offset1:199
	s_waitcnt lgkmcnt(0)
	v_cvt_pk_bf16_f32 v248, v232, v233
	v_cvt_pk_bf16_f32 v249, v234, v235
	v_cvt_pk_bf16_f32 v250, v236, v237
	v_cvt_pk_bf16_f32 v251, v238, v239
	v_cvt_pk_bf16_f32 v252, v240, v241
	v_cvt_pk_bf16_f32 v253, v242, v243
	v_cvt_pk_bf16_f32 v254, v244, v245
	v_cvt_pk_bf16_f32 v255, v246, v247
	global_store_dwordx4 v39, v[248:251], s[20:21]
	global_store_dwordx4 v39, v[252:255], s[20:21] offset:64
	v_add_u32_e32 v39, s53, v39
	s_waitcnt vmcnt(24)
	v_add_u32_e32 v40, s27, v37
	v_add_u32_e32 v40, 128, v40
	v_cmp_gt_u32_e32 vcc, s0, v40
	s_nop 1
	v_cndmask_b32_e32 v80, 0, v80, vcc
	v_cndmask_b32_e32 v81, 0, v81, vcc
	v_cndmask_b32_e32 v82, 0, v82, vcc
	v_cndmask_b32_e32 v83, 0, v83, vcc
	v_cndmask_b32_e32 v84, 0, v84, vcc
	v_cndmask_b32_e32 v85, 0, v85, vcc
	v_cndmask_b32_e32 v86, 0, v86, vcc
	v_cndmask_b32_e32 v87, 0, v87, vcc
	v_cndmask_b32_e32 v88, 0, v88, vcc
	v_cndmask_b32_e32 v89, 0, v89, vcc
	v_cndmask_b32_e32 v90, 0, v90, vcc
	v_cndmask_b32_e32 v91, 0, v91, vcc
	v_cndmask_b32_e32 v92, 0, v92, vcc
	v_cndmask_b32_e32 v93, 0, v93, vcc
	v_cndmask_b32_e32 v94, 0, v94, vcc
	v_cndmask_b32_e32 v95, 0, v95, vcc
	ds_write2_b32 v20, v80, v81 offset1:1
	ds_write2_b32 v20, v82, v83 offset0:2 offset1:3
	ds_write2_b32 v21, v84, v85 offset1:1
	ds_write2_b32 v21, v86, v87 offset0:2 offset1:3
	ds_write2_b32 v22, v88, v89 offset1:1
	ds_write2_b32 v22, v90, v91 offset0:2 offset1:3
	ds_write2_b32 v23, v92, v93 offset1:1
	ds_write2_b32 v23, v94, v95 offset0:2 offset1:3
	s_waitcnt lgkmcnt(0)
	s_barrier
	ds_read2_b32 v[232:233], v28 offset0:0 offset1:65
	ds_read2_b32 v[234:235], v28 offset0:130 offset1:195
	ds_read2_b32 v[236:237], v29 offset0:4 offset1:69
	ds_read2_b32 v[238:239], v29 offset0:134 offset1:199
	ds_read2_b32 v[240:241], v30 offset0:0 offset1:65
	ds_read2_b32 v[242:243], v30 offset0:130 offset1:195
	ds_read2_b32 v[244:245], v31 offset0:4 offset1:69
	ds_read2_b32 v[246:247], v31 offset0:134 offset1:199
	s_waitcnt lgkmcnt(0)
	v_cvt_pk_bf16_f32 v248, v232, v233
	v_cvt_pk_bf16_f32 v249, v234, v235
	v_cvt_pk_bf16_f32 v250, v236, v237
	v_cvt_pk_bf16_f32 v251, v238, v239
	v_cvt_pk_bf16_f32 v252, v240, v241
	v_cvt_pk_bf16_f32 v253, v242, v243
	v_cvt_pk_bf16_f32 v254, v244, v245
	v_cvt_pk_bf16_f32 v255, v246, v247
	global_store_dwordx4 v39, v[248:251], s[20:21]
	global_store_dwordx4 v39, v[252:255], s[20:21] offset:64
	v_add_u32_e32 v39, s53, v39
	s_waitcnt vmcnt(22)
	v_add_u32_e32 v40, s27, v37
	v_add_u32_e32 v40, 192, v40
	v_cmp_gt_u32_e32 vcc, s0, v40
	s_nop 1
	v_cndmask_b32_e32 v96, 0, v96, vcc
	v_cndmask_b32_e32 v97, 0, v97, vcc
	v_cndmask_b32_e32 v98, 0, v98, vcc
	v_cndmask_b32_e32 v99, 0, v99, vcc
	v_cndmask_b32_e32 v100, 0, v100, vcc
	v_cndmask_b32_e32 v101, 0, v101, vcc
	v_cndmask_b32_e32 v102, 0, v102, vcc
	v_cndmask_b32_e32 v103, 0, v103, vcc
	v_cndmask_b32_e32 v104, 0, v104, vcc
	v_cndmask_b32_e32 v105, 0, v105, vcc
	v_cndmask_b32_e32 v106, 0, v106, vcc
	v_cndmask_b32_e32 v107, 0, v107, vcc
	v_cndmask_b32_e32 v108, 0, v108, vcc
	v_cndmask_b32_e32 v109, 0, v109, vcc
	v_cndmask_b32_e32 v110, 0, v110, vcc
	v_cndmask_b32_e32 v111, 0, v111, vcc
	ds_write2_b32 v24, v96, v97 offset1:1
	ds_write2_b32 v24, v98, v99 offset0:2 offset1:3
	ds_write2_b32 v25, v100, v101 offset1:1
	ds_write2_b32 v25, v102, v103 offset0:2 offset1:3
	ds_write2_b32 v26, v104, v105 offset1:1
	ds_write2_b32 v26, v106, v107 offset0:2 offset1:3
	ds_write2_b32 v27, v108, v109 offset1:1
	ds_write2_b32 v27, v110, v111 offset0:2 offset1:3
	s_waitcnt lgkmcnt(0)
	s_barrier
	ds_read2_b32 v[232:233], v32 offset0:0 offset1:65
	ds_read2_b32 v[234:235], v32 offset0:130 offset1:195
	ds_read2_b32 v[236:237], v33 offset0:4 offset1:69
	ds_read2_b32 v[238:239], v33 offset0:134 offset1:199
	ds_read2_b32 v[240:241], v34 offset0:0 offset1:65
	ds_read2_b32 v[242:243], v34 offset0:130 offset1:195
	ds_read2_b32 v[244:245], v35 offset0:4 offset1:69
	ds_read2_b32 v[246:247], v35 offset0:134 offset1:199
	s_waitcnt lgkmcnt(0)
	v_cvt_pk_bf16_f32 v248, v232, v233
	v_cvt_pk_bf16_f32 v249, v234, v235
	v_cvt_pk_bf16_f32 v250, v236, v237
	v_cvt_pk_bf16_f32 v251, v238, v239
	v_cvt_pk_bf16_f32 v252, v240, v241
	v_cvt_pk_bf16_f32 v253, v242, v243
	v_cvt_pk_bf16_f32 v254, v244, v245
	v_cvt_pk_bf16_f32 v255, v246, v247
	global_store_dwordx4 v39, v[248:251], s[20:21]
	global_store_dwordx4 v39, v[252:255], s[20:21] offset:64
	v_add_u32_e32 v39, s53, v39
	s_waitcnt vmcnt(20)
	v_add_u32_e32 v40, s27, v37
	v_add_u32_e32 v40, 256, v40
	v_cmp_gt_u32_e32 vcc, s0, v40
	s_nop 1
	v_cndmask_b32_e32 v168, 0, v168, vcc
	v_cndmask_b32_e32 v169, 0, v169, vcc
	v_cndmask_b32_e32 v170, 0, v170, vcc
	v_cndmask_b32_e32 v171, 0, v171, vcc
	v_cndmask_b32_e32 v172, 0, v172, vcc
	v_cndmask_b32_e32 v173, 0, v173, vcc
	v_cndmask_b32_e32 v174, 0, v174, vcc
	v_cndmask_b32_e32 v175, 0, v175, vcc
	v_cndmask_b32_e32 v176, 0, v176, vcc
	v_cndmask_b32_e32 v177, 0, v177, vcc
	v_cndmask_b32_e32 v178, 0, v178, vcc
	v_cndmask_b32_e32 v179, 0, v179, vcc
	v_cndmask_b32_e32 v180, 0, v180, vcc
	v_cndmask_b32_e32 v181, 0, v181, vcc
	v_cndmask_b32_e32 v182, 0, v182, vcc
	v_cndmask_b32_e32 v183, 0, v183, vcc
	ds_write2_b32 v20, v168, v169 offset1:1
	ds_write2_b32 v20, v170, v171 offset0:2 offset1:3
	ds_write2_b32 v21, v172, v173 offset1:1
	ds_write2_b32 v21, v174, v175 offset0:2 offset1:3
	ds_write2_b32 v22, v176, v177 offset1:1
	ds_write2_b32 v22, v178, v179 offset0:2 offset1:3
	ds_write2_b32 v23, v180, v181 offset1:1
	ds_write2_b32 v23, v182, v183 offset0:2 offset1:3
	s_waitcnt lgkmcnt(0)
	s_barrier
	ds_read2_b32 v[232:233], v28 offset0:0 offset1:65
	ds_read2_b32 v[234:235], v28 offset0:130 offset1:195
	ds_read2_b32 v[236:237], v29 offset0:4 offset1:69
	ds_read2_b32 v[238:239], v29 offset0:134 offset1:199
	ds_read2_b32 v[240:241], v30 offset0:0 offset1:65
	ds_read2_b32 v[242:243], v30 offset0:130 offset1:195
	ds_read2_b32 v[244:245], v31 offset0:4 offset1:69
	ds_read2_b32 v[246:247], v31 offset0:134 offset1:199
	s_waitcnt lgkmcnt(0)
	v_cvt_pk_bf16_f32 v248, v232, v233
	v_cvt_pk_bf16_f32 v249, v234, v235
	v_cvt_pk_bf16_f32 v250, v236, v237
	v_cvt_pk_bf16_f32 v251, v238, v239
	v_cvt_pk_bf16_f32 v252, v240, v241
	v_cvt_pk_bf16_f32 v253, v242, v243
	v_cvt_pk_bf16_f32 v254, v244, v245
	v_cvt_pk_bf16_f32 v255, v246, v247
	global_store_dwordx4 v39, v[248:251], s[20:21]
	global_store_dwordx4 v39, v[252:255], s[20:21] offset:64
	v_add_u32_e32 v39, s53, v39
	s_waitcnt vmcnt(18)
	v_add_u32_e32 v40, s27, v37
	v_add_u32_e32 v40, 320, v40
	v_cmp_gt_u32_e32 vcc, s0, v40
	s_nop 1
	v_cndmask_b32_e32 v184, 0, v184, vcc
	v_cndmask_b32_e32 v185, 0, v185, vcc
	v_cndmask_b32_e32 v186, 0, v186, vcc
	v_cndmask_b32_e32 v187, 0, v187, vcc
	v_cndmask_b32_e32 v188, 0, v188, vcc
	v_cndmask_b32_e32 v189, 0, v189, vcc
	v_cndmask_b32_e32 v190, 0, v190, vcc
	v_cndmask_b32_e32 v191, 0, v191, vcc
	v_cndmask_b32_e32 v192, 0, v192, vcc
	v_cndmask_b32_e32 v193, 0, v193, vcc
	v_cndmask_b32_e32 v194, 0, v194, vcc
	v_cndmask_b32_e32 v195, 0, v195, vcc
	v_cndmask_b32_e32 v196, 0, v196, vcc
	v_cndmask_b32_e32 v197, 0, v197, vcc
	v_cndmask_b32_e32 v198, 0, v198, vcc
	v_cndmask_b32_e32 v199, 0, v199, vcc
	ds_write2_b32 v24, v184, v185 offset1:1
	ds_write2_b32 v24, v186, v187 offset0:2 offset1:3
	ds_write2_b32 v25, v188, v189 offset1:1
	ds_write2_b32 v25, v190, v191 offset0:2 offset1:3
	ds_write2_b32 v26, v192, v193 offset1:1
	ds_write2_b32 v26, v194, v195 offset0:2 offset1:3
	ds_write2_b32 v27, v196, v197 offset1:1
	ds_write2_b32 v27, v198, v199 offset0:2 offset1:3
	s_waitcnt lgkmcnt(0)
	s_barrier
	ds_read2_b32 v[232:233], v32 offset0:0 offset1:65
	ds_read2_b32 v[234:235], v32 offset0:130 offset1:195
	ds_read2_b32 v[236:237], v33 offset0:4 offset1:69
	ds_read2_b32 v[238:239], v33 offset0:134 offset1:199
	ds_read2_b32 v[240:241], v34 offset0:0 offset1:65
	ds_read2_b32 v[242:243], v34 offset0:130 offset1:195
	ds_read2_b32 v[244:245], v35 offset0:4 offset1:69
	ds_read2_b32 v[246:247], v35 offset0:134 offset1:199
	s_waitcnt lgkmcnt(0)
	v_cvt_pk_bf16_f32 v248, v232, v233
	v_cvt_pk_bf16_f32 v249, v234, v235
	v_cvt_pk_bf16_f32 v250, v236, v237
	v_cvt_pk_bf16_f32 v251, v238, v239
	v_cvt_pk_bf16_f32 v252, v240, v241
	v_cvt_pk_bf16_f32 v253, v242, v243
	v_cvt_pk_bf16_f32 v254, v244, v245
	v_cvt_pk_bf16_f32 v255, v246, v247
	global_store_dwordx4 v39, v[248:251], s[20:21]
	global_store_dwordx4 v39, v[252:255], s[20:21] offset:64
	v_add_u32_e32 v39, s53, v39
	s_waitcnt vmcnt(16)
	v_add_u32_e32 v40, s27, v37
	v_add_u32_e32 v40, 384, v40
	v_cmp_gt_u32_e32 vcc, s0, v40
	s_nop 1
	v_cndmask_b32_e32 v200, 0, v200, vcc
	v_cndmask_b32_e32 v201, 0, v201, vcc
	v_cndmask_b32_e32 v202, 0, v202, vcc
	v_cndmask_b32_e32 v203, 0, v203, vcc
	v_cndmask_b32_e32 v204, 0, v204, vcc
	v_cndmask_b32_e32 v205, 0, v205, vcc
	v_cndmask_b32_e32 v206, 0, v206, vcc
	v_cndmask_b32_e32 v207, 0, v207, vcc
	v_cndmask_b32_e32 v208, 0, v208, vcc
	v_cndmask_b32_e32 v209, 0, v209, vcc
	v_cndmask_b32_e32 v210, 0, v210, vcc
	v_cndmask_b32_e32 v211, 0, v211, vcc
	v_cndmask_b32_e32 v212, 0, v212, vcc
	v_cndmask_b32_e32 v213, 0, v213, vcc
	v_cndmask_b32_e32 v214, 0, v214, vcc
	v_cndmask_b32_e32 v215, 0, v215, vcc
	ds_write2_b32 v20, v200, v201 offset1:1
	ds_write2_b32 v20, v202, v203 offset0:2 offset1:3
	ds_write2_b32 v21, v204, v205 offset1:1
	ds_write2_b32 v21, v206, v207 offset0:2 offset1:3
	ds_write2_b32 v22, v208, v209 offset1:1
	ds_write2_b32 v22, v210, v211 offset0:2 offset1:3
	ds_write2_b32 v23, v212, v213 offset1:1
	ds_write2_b32 v23, v214, v215 offset0:2 offset1:3
	s_waitcnt lgkmcnt(0)
	s_barrier
	ds_read2_b32 v[232:233], v28 offset0:0 offset1:65
	ds_read2_b32 v[234:235], v28 offset0:130 offset1:195
	ds_read2_b32 v[236:237], v29 offset0:4 offset1:69
	ds_read2_b32 v[238:239], v29 offset0:134 offset1:199
	ds_read2_b32 v[240:241], v30 offset0:0 offset1:65
	ds_read2_b32 v[242:243], v30 offset0:130 offset1:195
	ds_read2_b32 v[244:245], v31 offset0:4 offset1:69
	ds_read2_b32 v[246:247], v31 offset0:134 offset1:199
	s_waitcnt lgkmcnt(0)
	v_cvt_pk_bf16_f32 v248, v232, v233
	v_cvt_pk_bf16_f32 v249, v234, v235
	v_cvt_pk_bf16_f32 v250, v236, v237
	v_cvt_pk_bf16_f32 v251, v238, v239
	v_cvt_pk_bf16_f32 v252, v240, v241
	v_cvt_pk_bf16_f32 v253, v242, v243
	v_cvt_pk_bf16_f32 v254, v244, v245
	v_cvt_pk_bf16_f32 v255, v246, v247
	global_store_dwordx4 v39, v[248:251], s[20:21]
	global_store_dwordx4 v39, v[252:255], s[20:21] offset:64
	v_add_u32_e32 v39, s53, v39
	s_waitcnt vmcnt(14)
	v_add_u32_e32 v40, s27, v37
	v_add_u32_e32 v40, 448, v40
	v_cmp_gt_u32_e32 vcc, s0, v40
	s_nop 1
	v_cndmask_b32_e32 v216, 0, v216, vcc
	v_cndmask_b32_e32 v217, 0, v217, vcc
	v_cndmask_b32_e32 v218, 0, v218, vcc
	v_cndmask_b32_e32 v219, 0, v219, vcc
	v_cndmask_b32_e32 v220, 0, v220, vcc
	v_cndmask_b32_e32 v221, 0, v221, vcc
	v_cndmask_b32_e32 v222, 0, v222, vcc
	v_cndmask_b32_e32 v223, 0, v223, vcc
	v_cndmask_b32_e32 v224, 0, v224, vcc
	v_cndmask_b32_e32 v225, 0, v225, vcc
	v_cndmask_b32_e32 v226, 0, v226, vcc
	v_cndmask_b32_e32 v227, 0, v227, vcc
	v_cndmask_b32_e32 v228, 0, v228, vcc
	v_cndmask_b32_e32 v229, 0, v229, vcc
	v_cndmask_b32_e32 v230, 0, v230, vcc
	v_cndmask_b32_e32 v231, 0, v231, vcc
	ds_write2_b32 v24, v216, v217 offset1:1
	ds_write2_b32 v24, v218, v219 offset0:2 offset1:3
	ds_write2_b32 v25, v220, v221 offset1:1
	ds_write2_b32 v25, v222, v223 offset0:2 offset1:3
	ds_write2_b32 v26, v224, v225 offset1:1
	ds_write2_b32 v26, v226, v227 offset0:2 offset1:3
	ds_write2_b32 v27, v228, v229 offset1:1
	ds_write2_b32 v27, v230, v231 offset0:2 offset1:3
	s_waitcnt lgkmcnt(0)
	s_barrier
	ds_read2_b32 v[232:233], v32 offset0:0 offset1:65
	ds_read2_b32 v[234:235], v32 offset0:130 offset1:195
	ds_read2_b32 v[236:237], v33 offset0:4 offset1:69
	ds_read2_b32 v[238:239], v33 offset0:134 offset1:199
	ds_read2_b32 v[240:241], v34 offset0:0 offset1:65
	ds_read2_b32 v[242:243], v34 offset0:130 offset1:195
	ds_read2_b32 v[244:245], v35 offset0:4 offset1:69
	ds_read2_b32 v[246:247], v35 offset0:134 offset1:199
	s_waitcnt lgkmcnt(0)
	v_cvt_pk_bf16_f32 v248, v232, v233
	v_cvt_pk_bf16_f32 v249, v234, v235
	v_cvt_pk_bf16_f32 v250, v236, v237
	v_cvt_pk_bf16_f32 v251, v238, v239
	v_cvt_pk_bf16_f32 v252, v240, v241
	v_cvt_pk_bf16_f32 v253, v242, v243
	v_cvt_pk_bf16_f32 v254, v244, v245
	v_cvt_pk_bf16_f32 v255, v246, v247
	global_store_dwordx4 v39, v[248:251], s[20:21]
	global_store_dwordx4 v39, v[252:255], s[20:21] offset:64
	s_waitcnt lgkmcnt(0)
	s_barrier
	s_mov_b64 s[20:21], 0
	s_branch .LBB0_54

.LBB0_96:
	s_waitcnt vmcnt(0) lgkmcnt(0)
	v_mov_b32_e32 v1, 0
	v_mov_b32_e32 v3, 1
	v_readlane_b32 s20, v162, 60
	s_lshl_b32 s2, s40, 8
	s_add_u32 s2, s84, s2
	s_addc_u32 s3, s85, 0
	s_add_u32 s2, s2, 0x1440
	s_addc_u32 s3, s3, 0
	s_add_u32 s20, s20, 1
	s_nop 2
	v_writelane_b32 v162, s20, 60
	v_readlane_b32 s21, v164, 0
	s_nop 1
	s_sub_u32 s21, s40, s21
	s_and_b32 s21, s21, 7
	s_lshl_b32 s21, 1, s21
	v_mov_b32_e32 v5, s21
	s_add_u32 s24, s84, 0x3480
	s_addc_u32 s25, s85, 0
	global_atomic_or v5, v1, v5, s[24:25] sc0
	s_waitcnt vmcnt(0)
	global_atomic_add v4, v1, v3, s[2:3] sc0
	v_mul_lo_u32 v2, v2, s20
	v_mul_lo_u32 v0, v0, s20
	s_add_u32 s22, s84, 0x3440
	s_addc_u32 s23, s85, 0
	s_waitcnt vmcnt(0)
	v_add_u32_e32 v4, 1, v4
	s_nop 0
	v_cmp_eq_u32_e32 vcc, v4, v2
	s_nop 3
	s_cbranch_vccz .Lxb20_poll
	buffer_wbl2 sc1
	s_waitcnt vmcnt(0)
	global_atomic_add v1, v3, s[22:23]

.Lxb20_done:
	global_load_dword v4, v1, s[24:25] sc1
	s_waitcnt vmcnt(0)
	v_readfirstlane_b32 s21, v4
	s_bcnt1_i32_b32 s21, s21
	s_cmp_eq_u32 s21, 1
	s_cselect_b32 s21, 1, 0
	s_cmp_eq_u32 s46, 0x200
	s_cselect_b32 s21, s21, 0
	s_nop 0
	v_writelane_b32 v162, s21, 62

.LBB0_131:
.LBB0_132:
	s_mov_b64 s[0:1], exec
	s_lshl_b32 s34, s46, 2
	v_readlane_b32 s10, v164, 0
	s_mov_b32 s11, s46
	v_lshrrev_b32_e32 v80, 6, v128
	v_and_b32_e32 v81, 63, v128
	v_readlane_b32 s16, v163, 13
	v_readlane_b32 s17, v163, 14
	v_readlane_b32 s18, v163, 15
	v_readlane_b32 s19, v163, 16
	v_readlane_b32 s28, v164, 1
	v_readlane_b32 s29, v164, 2
	v_readlane_b32 s30, v164, 3
	v_readlane_b32 s31, v164, 4
	v_readfirstlane_b32 s12, v80
	v_lshlrev_b32_e32 v82, 4, v81
	v_lshlrev_b32_e32 v83, 5, v81
	v_mov_b32_e32 v98, 0x358637bd
	s_lshl_b32 s13, s10, 2
	s_add_u32 s13, s13, s12
	s_lshl_b32 s14, s11, 2
	s_mul_i32 s35, s14, 5
	s_cmp_lg_u32 s11, 0x200
	s_cbranch_scc1 .Lgro0_rm_done
	s_and_b32 s4, s10, 7
	s_lshl_b32 s4, s4, 3
	s_bfe_u32 s32, s10, 0x30003
	s_or_b32 s4, s4, s32
	s_mul_i32 s4, s4, 0xa0
	s_lshr_b32 s32, s10, 6
	s_mul_i32 s32, s32, 20
	s_add_u32 s4, s4, s32
	s_mul_i32 s32, s12, 5
	s_add_u32 s13, s4, s32
	s_mov_b32 s14, 1
	s_mov_b32 s35, 0x2800
.Lgro0_rm_done:
.Lgro0_batch:
	s_mov_b32 s20, s13
	s_min_u32 s21, s20, 0x27ff
	s_sub_u32 s4, s21, 0x2000
	s_cmp_lt_u32 s21, 0x2000
	s_cselect_b32 s4, s21, s4
	s_cselect_b32 s22, s28, s30
	s_cselect_b32 s23, s29, s31
	s_lshl_b32 s4, s4, 12
	s_add_u32 s22, s22, s4
	s_addc_u32 s23, s23, 0
	global_load_dwordx4 v[168:171], v83, s[22:23]
	global_load_dwordx4 v[172:175], v83, s[22:23] offset:16
	global_load_dwordx4 v[176:179], v83, s[22:23] offset:2048
	global_load_dwordx4 v[180:183], v83, s[22:23] offset:2064
	s_add_u32 s20, s20, s14
	s_min_u32 s21, s20, 0x27ff
	s_sub_u32 s4, s21, 0x2000
	s_cmp_lt_u32 s21, 0x2000
	s_cselect_b32 s4, s21, s4
	s_cselect_b32 s22, s28, s30
	s_cselect_b32 s23, s29, s31
	s_lshl_b32 s4, s4, 12
	s_add_u32 s22, s22, s4
	s_addc_u32 s23, s23, 0
	global_load_dwordx4 v[184:187], v83, s[22:23]
	global_load_dwordx4 v[188:191], v83, s[22:23] offset:16
	global_load_dwordx4 v[192:195], v83, s[22:23] offset:2048
	global_load_dwordx4 v[196:199], v83, s[22:23] offset:2064
	s_add_u32 s20, s20, s14
	s_min_u32 s21, s20, 0x27ff
	s_sub_u32 s4, s21, 0x2000
	s_cmp_lt_u32 s21, 0x2000
	s_cselect_b32 s4, s21, s4
	s_cselect_b32 s22, s28, s30
	s_cselect_b32 s23, s29, s31
	s_lshl_b32 s4, s4, 12
	s_add_u32 s22, s22, s4
	s_addc_u32 s23, s23, 0
	global_load_dwordx4 v[200:203], v83, s[22:23]
	global_load_dwordx4 v[204:207], v83, s[22:23] offset:16
	global_load_dwordx4 v[208:211], v83, s[22:23] offset:2048
	global_load_dwordx4 v[212:215], v83, s[22:23] offset:2064
	s_add_u32 s20, s20, s14
	s_min_u32 s21, s20, 0x27ff
	s_sub_u32 s4, s21, 0x2000
	s_cmp_lt_u32 s21, 0x2000
	s_cselect_b32 s4, s21, s4
	s_cselect_b32 s22, s28, s30
	s_cselect_b32 s23, s29, s31
	s_lshl_b32 s4, s4, 12
	s_add_u32 s22, s22, s4
	s_addc_u32 s23, s23, 0
	global_load_dwordx4 v[216:219], v83, s[22:23]
	global_load_dwordx4 v[220:223], v83, s[22:23] offset:16
	global_load_dwordx4 v[224:227], v83, s[22:23] offset:2048
	global_load_dwordx4 v[228:231], v83, s[22:23] offset:2064
	s_add_u32 s20, s20, s14
	s_min_u32 s21, s20, 0x27ff
	s_sub_u32 s4, s21, 0x2000
	s_cmp_lt_u32 s21, 0x2000
	s_cselect_b32 s4, s21, s4
	s_cselect_b32 s22, s28, s30
	s_cselect_b32 s23, s29, s31
	s_lshl_b32 s4, s4, 12
	s_add_u32 s22, s22, s4
	s_addc_u32 s23, s23, 0
	global_load_dwordx4 v[232:235], v83, s[22:23]
	global_load_dwordx4 v[236:239], v83, s[22:23] offset:16
	global_load_dwordx4 v[240:243], v83, s[22:23] offset:2048
	global_load_dwordx4 v[244:247], v83, s[22:23] offset:2064
	s_mov_b32 s15, -1
	s_mov_b32 s20, s13
	s_cmp_ge_u32 s20, 0x2800
	s_cbranch_scc1 .Lgro0_bend
	s_sub_u32 s4, s20, 0x2000
	s_lshr_b32 s4, s4, 10
	s_add_u32 s4, s4, 1
	s_cmp_lt_u32 s20, 0x2000
	s_cselect_b32 s4, 0, s4
	s_cmp_eq_u32 s4, s15
	s_cbranch_scc1 .Lgro0_r0_same
	s_mov_b32 s15, s4
	s_mul_i32 s4, s4, 0x9000
	s_add_u32 s22, s16, s4
	s_addc_u32 s23, s17, 0
	global_load_dwordx4 v[16:19], v83, s[22:23]
	global_load_dwordx4 v[20:23], v83, s[22:23] offset:16
	global_load_dwordx4 v[24:27], v83, s[22:23] offset:2048
	global_load_dwordx4 v[28:31], v83, s[22:23] offset:2064
	s_add_u32 s22, s22, 0x1000
	s_addc_u32 s23, s23, 0
	global_load_dwordx4 v[32:35], v83, s[22:23]
	global_load_dwordx4 v[36:39], v83, s[22:23] offset:16
	global_load_dwordx4 v[40:43], v83, s[22:23] offset:2048
	global_load_dwordx4 v[44:47], v83, s[22:23] offset:2064
	s_waitcnt vmcnt(0)
	s_branch .Lgro0_r0_go

.Lgro0_bend:
	s_add_u32 s13, s13, s35
	s_cmp_lt_u32 s13, 0x2800
	s_cbranch_scc1 .Lgro0_batch

.LBB0_152:
	s_waitcnt vmcnt(0) lgkmcnt(0)
	v_mov_b32_e32 v1, 0
	v_mov_b32_e32 v3, 1
	v_readlane_b32 s20, v162, 60
	s_lshl_b32 s2, s40, 8
	s_add_u32 s2, s84, s2
	s_addc_u32 s3, s85, 0
	s_add_u32 s2, s2, 0x1440
	s_addc_u32 s3, s3, 0
	s_add_u32 s20, s20, 1
	s_nop 2
	v_writelane_b32 v162, s20, 60
	global_atomic_add v4, v1, v3, s[2:3] sc0
	v_mul_lo_u32 v2, v2, s20
	v_mul_lo_u32 v0, v0, s20
	s_add_u32 s22, s84, 0x3440
	s_addc_u32 s23, s85, 0
	s_waitcnt vmcnt(0)
	v_add_u32_e32 v4, 1, v4
	s_nop 0
	v_cmp_eq_u32_e32 vcc, v4, v2
	s_nop 3
	s_cbranch_vccz .Lxb21_poll
	v_readlane_b32 s21, v162, 62
	s_nop 1
	s_cmp_eq_u32 s21, 1
	s_cbranch_scc1 .Lxb21_nowb
	buffer_wbl2 sc1
	s_waitcnt vmcnt(0)
.Lxb21_nowb:
	global_atomic_add v1, v3, s[22:23]

.Lxb0_ninv:
	s_barrier
	s_and_saveexec_b64 s[2:3], s[4:5]
	s_cbranch_execz .LBB0_246
	s_waitcnt vmcnt(0) lgkmcnt(0)
	ds_read_b32 v2, v117 offset:53248
	ds_read_b32 v3, v117 offset:53252
	v_readlane_b32 s4, v163, 62
	v_readlane_b32 s5, v163, 63
	v_readlane_b32 s36, v162, 60
	s_nop 1
	s_add_u32 s36, s36, 1
	s_nop 2
	v_writelane_b32 v162, s36, 60
	global_atomic_add v0, v117, v129, s[4:5] offset:64 sc0
	s_waitcnt lgkmcnt(0)
	v_lshrrev_b32_e32 v4, 1, v2
	v_mul_lo_u32 v2, v2, s36
	v_mul_lo_u32 v3, v3, s36
	v_readlane_b32 s4, v162, 2
	v_readlane_b32 s5, v162, 3
	s_waitcnt vmcnt(0)
	v_add_u32_e32 v0, 1, v0
	s_nop 0
	v_cmp_eq_u32_e32 vcc, v0, v2
	s_nop 3
	s_cbranch_vccz .Lxb0_poll
	v_readlane_b32 s20, v162, 62
	s_nop 1
	s_cmp_eq_u32 s20, 1
	s_cbranch_scc1 .Lxb0_nowb
	buffer_wbl2 sc1
	s_waitcnt vmcnt(0)
.Lxb0_nowb:
	global_atomic_add v117, v129, s[4:5] offset:64

.LBB0_319:
	s_andn2_b64 vcc, exec, s[2:3]
	s_cbranch_vccnz .LBB0_373
	v_readlane_b32 s10, v164, 0
	v_readlane_b32 s11, v162, 14
	v_lshrrev_b32_e32 v80, 6, v128
	v_and_b32_e32 v81, 63, v128
	v_readlane_b32 s16, v163, 13
	v_readlane_b32 s17, v163, 14
	v_readlane_b32 s18, v163, 15
	v_readlane_b32 s19, v163, 16
	v_readfirstlane_b32 s12, v80
	v_lshlrev_b32_e32 v82, 4, v81
	v_lshlrev_b32_e32 v83, 5, v81
	s_lshl_b32 s13, s10, 2
	s_add_u32 s13, s13, s12
	s_lshl_b32 s14, s11, 2
	s_mul_i32 s36, s14, 5
	s_cmp_lg_u32 s11, 0x200
	s_cbranch_scc1 .Lgro2_rm_done
	s_and_b32 s4, s10, 7
	s_lshl_b32 s4, s4, 3
	s_bfe_u32 s32, s10, 0x30003
	s_or_b32 s4, s4, s32
	s_mul_i32 s4, s4, 0xa0
	s_lshr_b32 s32, s10, 6
	s_mul_i32 s32, s32, 20
	s_add_u32 s4, s4, s32
	s_mul_i32 s32, s12, 5
	s_add_u32 s13, s4, s32
	s_mov_b32 s14, 1
	s_mov_b32 s36, 0x2800
.Lgro2_rm_done:
	s_mul_i32 s4, s34, 0x1b000
	s_add_u32 s6, s4, 0x2000
	s_add_u32 s7, s4, 0x3000

.Lgro2_bend:
	s_add_u32 s13, s13, s36
	s_cmp_lt_u32 s13, 0x2800
	s_cbranch_scc1 .Lgro2_batch

.Lxb3_ninv:
	s_barrier
	s_and_saveexec_b64 s[2:3], s[4:5]
	s_cbranch_execz .LBB0_520
	s_waitcnt vmcnt(0) lgkmcnt(0)
	ds_read_b32 v2, v117 offset:53248
	ds_read_b32 v3, v117 offset:53252
	v_readlane_b32 s4, v163, 62
	v_readlane_b32 s5, v163, 63
	v_readlane_b32 s36, v162, 60
	s_nop 1
	s_add_u32 s36, s36, 1
	s_nop 2
	v_writelane_b32 v162, s36, 60
	global_atomic_add v0, v117, v129, s[4:5] offset:64 sc0
	s_waitcnt lgkmcnt(0)
	v_lshrrev_b32_e32 v4, 1, v2
	v_mul_lo_u32 v2, v2, s36
	v_mul_lo_u32 v3, v3, s36
	v_readlane_b32 s4, v162, 2
	v_readlane_b32 s5, v162, 3
	s_waitcnt vmcnt(0)
	v_add_u32_e32 v0, 1, v0
	s_nop 0
	v_cmp_eq_u32_e32 vcc, v0, v2
	s_nop 3
	s_cbranch_vccz .Lxb3_poll
	buffer_wbl2 sc1
	s_waitcnt vmcnt(0)
	global_atomic_add v117, v129, s[4:5] offset:64

.LBB0_625:
	s_and_b32 s38, 0xffff, s36
	v_cvt_f32_u32_e32 v0, s38
	s_and_b32 s38, s3, 0xffff
	v_cvt_f32_u32_e32 v1, s38
	s_waitcnt vmcnt(5)
	v_mov_b32_e32 v8, v128
	v_rcp_iflag_f32_e32 v2, v0
	v_mov_b32_e32 v4, 0
	v_ashrrev_i32_e32 v9, 4, v8
	v_mul_f32_e32 v2, v1, v2
	v_trunc_f32_e32 v2, v2
	v_cvt_u32_f32_e32 v3, v2
	v_fma_f32 v1, -v2, v0, v1
	v_cmp_ge_f32_e64 s[38:39], |v1|, v0
	s_cmp_lg_u64 s[38:39], 0
	v_readfirstlane_b32 s38, v3
	s_addc_u32 s38, s38, 0
	s_and_b32 s39, s38, 0xffff
	s_mul_i32 s38, s38, s36
	s_sub_i32 s3, s3, s38
	s_lshl_b32 s3, s3, 6
	v_lshlrev_b32_e32 v0, 2, v8
	s_and_b32 s3, s3, 0xffc0
	v_and_b32_e32 v1, 60, v0
	v_or_b32_e32 v0, s3, v1
	v_lshlrev_b32_e32 v116, 2, v0
	s_lshl_b32 s36, s39, 6
	v_cmp_gt_u32_e32 vcc, s2, v0
	v_lshl_add_u64 v[6:7], s[24:25], 0, v[116:117]
	v_lshrrev_b32_e32 v36, 4, v128
	v_and_b32_e32 v37, 15, v128
	v_lshlrev_b32_e32 v37, 2, v37
	s_movk_i32 s50, 0x104
	v_mul_lo_u32 v41, v36, s50
	v_lshl_add_u32 v20, v37, 2, v41
	v_add_u32_e32 v21, 0x1040, v20
	v_add_u32_e32 v22, 0x2080, v20
	v_add_u32_e32 v23, 0x30c0, v20
	v_add_u32_e32 v24, 0x4200, v20
	v_add_u32_e32 v25, 0x4200, v21
	v_add_u32_e32 v26, 0x4200, v22
	v_add_u32_e32 v27, 0x4200, v23
	v_and_b32_e32 v41, 3, v128
	v_lshlrev_b32_e32 v41, 3, v41
	v_mul_lo_u32 v28, v41, s50
	v_and_b32_e32 v42, -4, v128
	v_add_u32_e32 v28, v28, v42
	v_add_u32_e32 v29, 0x400, v28
	v_add_u32_e32 v30, 0x2080, v28
	v_add_u32_e32 v31, 0x2480, v28
	v_add_u32_e32 v32, 0x4200, v28
	v_add_u32_e32 v33, 0x4200, v29
	v_add_u32_e32 v34, 0x4200, v30
	v_add_u32_e32 v35, 0x4200, v31
	v_add_u32_e32 v38, s36, v36
	v_mul_lo_u32 v38, v38, s2
	v_lshlrev_b32_e32 v38, 2, v38
	s_lshl_b32 s51, s2, 6
	s_sub_u32 s52, s2, 4
	v_lshrrev_b32_e32 v39, 2, v128
	v_add_u32_e32 v39, s3, v39
	v_mul_lo_u32 v39, v39, s22
	v_add_u32_e32 v39, s36, v39
	v_add_u32_e32 v39, v41, v39
	v_lshlrev_b32_e32 v39, 1, v39
	s_lshl_b32 s53, s22, 7
	v_add_u32_e32 v40, s3, v37
	v_min_u32_e32 v40, s52, v40
	v_lshl_add_u32 v112, v40, 2, v38
	v_add_u32_e32 v113, s51, v112
	v_add_u32_e32 v114, s51, v113
	v_add_u32_e32 v115, s51, v114
	global_load_dwordx4 v[48:51], v112, s[24:25] nt
	global_load_dwordx4 v[52:55], v113, s[24:25] nt
	global_load_dwordx4 v[56:59], v114, s[24:25] nt
	global_load_dwordx4 v[60:63], v115, s[24:25] nt
	v_add_u32_e32 v40, s3, v37
	v_add_u32_e32 v40, 64, v40
	v_min_u32_e32 v40, s52, v40
	v_lshl_add_u32 v112, v40, 2, v38
	v_add_u32_e32 v113, s51, v112
	v_add_u32_e32 v114, s51, v113
	v_add_u32_e32 v115, s51, v114
	global_load_dwordx4 v[64:67], v112, s[24:25] nt
	global_load_dwordx4 v[68:71], v113, s[24:25] nt
	global_load_dwordx4 v[72:75], v114, s[24:25] nt
	global_load_dwordx4 v[76:79], v115, s[24:25] nt
	v_add_u32_e32 v40, s3, v37
	v_add_u32_e32 v40, 128, v40
	v_min_u32_e32 v40, s52, v40
	v_lshl_add_u32 v112, v40, 2, v38
	v_add_u32_e32 v113, s51, v112
	v_add_u32_e32 v114, s51, v113
	v_add_u32_e32 v115, s51, v114
	global_load_dwordx4 v[80:83], v112, s[24:25] nt
	global_load_dwordx4 v[84:87], v113, s[24:25] nt
	global_load_dwordx4 v[88:91], v114, s[24:25] nt
	global_load_dwordx4 v[92:95], v115, s[24:25] nt
	v_add_u32_e32 v40, s3, v37
	v_add_u32_e32 v40, 192, v40
	v_min_u32_e32 v40, s52, v40
	v_lshl_add_u32 v112, v40, 2, v38
	v_add_u32_e32 v113, s51, v112
	v_add_u32_e32 v114, s51, v113
	v_add_u32_e32 v115, s51, v114
	global_load_dwordx4 v[96:99], v112, s[24:25] nt
	global_load_dwordx4 v[100:103], v113, s[24:25] nt
	global_load_dwordx4 v[104:107], v114, s[24:25] nt
	global_load_dwordx4 v[108:111], v115, s[24:25] nt
	v_add_u32_e32 v40, s3, v37
	v_add_u32_e32 v40, 256, v40
	v_min_u32_e32 v40, s52, v40
	v_lshl_add_u32 v112, v40, 2, v38
	v_add_u32_e32 v113, s51, v112
	v_add_u32_e32 v114, s51, v113
	v_add_u32_e32 v115, s51, v114
	global_load_dwordx4 v[168:171], v112, s[24:25] nt
	global_load_dwordx4 v[172:175], v113, s[24:25] nt
	global_load_dwordx4 v[176:179], v114, s[24:25] nt
	global_load_dwordx4 v[180:183], v115, s[24:25] nt
	v_add_u32_e32 v40, s3, v37
	v_add_u32_e32 v40, 320, v40
	v_min_u32_e32 v40, s52, v40
	v_lshl_add_u32 v112, v40, 2, v38
	v_add_u32_e32 v113, s51, v112
	v_add_u32_e32 v114, s51, v113
	v_add_u32_e32 v115, s51, v114
	global_load_dwordx4 v[184:187], v112, s[24:25] nt
	global_load_dwordx4 v[188:191], v113, s[24:25] nt
	global_load_dwordx4 v[192:195], v114, s[24:25] nt
	global_load_dwordx4 v[196:199], v115, s[24:25] nt
	v_add_u32_e32 v40, s3, v37
	v_add_u32_e32 v40, 384, v40
	v_min_u32_e32 v40, s52, v40
	v_lshl_add_u32 v112, v40, 2, v38
	v_add_u32_e32 v113, s51, v112
	v_add_u32_e32 v114, s51, v113
	v_add_u32_e32 v115, s51, v114
	global_load_dwordx4 v[200:203], v112, s[24:25] nt
	global_load_dwordx4 v[204:207], v113, s[24:25] nt
	global_load_dwordx4 v[208:211], v114, s[24:25] nt
	global_load_dwordx4 v[212:215], v115, s[24:25] nt
	v_add_u32_e32 v40, s3, v37
	v_add_u32_e32 v40, 448, v40
	v_min_u32_e32 v40, s52, v40
	v_lshl_add_u32 v112, v40, 2, v38
	v_add_u32_e32 v113, s51, v112
	v_add_u32_e32 v114, s51, v113
	v_add_u32_e32 v115, s51, v114
	global_load_dwordx4 v[216:219], v112, s[24:25] nt
	global_load_dwordx4 v[220:223], v113, s[24:25] nt
	global_load_dwordx4 v[224:227], v114, s[24:25] nt
	global_load_dwordx4 v[228:231], v115, s[24:25] nt
	s_waitcnt vmcnt(28)
	v_add_u32_e32 v40, s3, v37
	v_cmp_gt_u32_e32 vcc, s2, v40
	s_nop 1
	v_cndmask_b32_e32 v48, 0, v48, vcc
	v_cndmask_b32_e32 v49, 0, v49, vcc
	v_cndmask_b32_e32 v50, 0, v50, vcc
	v_cndmask_b32_e32 v51, 0, v51, vcc
	v_cndmask_b32_e32 v52, 0, v52, vcc
	v_cndmask_b32_e32 v53, 0, v53, vcc
	v_cndmask_b32_e32 v54, 0, v54, vcc
	v_cndmask_b32_e32 v55, 0, v55, vcc
	v_cndmask_b32_e32 v56, 0, v56, vcc
	v_cndmask_b32_e32 v57, 0, v57, vcc
	v_cndmask_b32_e32 v58, 0, v58, vcc
	v_cndmask_b32_e32 v59, 0, v59, vcc
	v_cndmask_b32_e32 v60, 0, v60, vcc
	v_cndmask_b32_e32 v61, 0, v61, vcc
	v_cndmask_b32_e32 v62, 0, v62, vcc
	v_cndmask_b32_e32 v63, 0, v63, vcc
	ds_write2_b32 v20, v48, v49 offset1:1
	ds_write2_b32 v20, v50, v51 offset0:2 offset1:3
	ds_write2_b32 v21, v52, v53 offset1:1
	ds_write2_b32 v21, v54, v55 offset0:2 offset1:3
	ds_write2_b32 v22, v56, v57 offset1:1
	ds_write2_b32 v22, v58, v59 offset0:2 offset1:3
	ds_write2_b32 v23, v60, v61 offset1:1
	ds_write2_b32 v23, v62, v63 offset0:2 offset1:3
	s_waitcnt lgkmcnt(0)
	s_barrier
	ds_read2_b32 v[232:233], v28 offset0:0 offset1:65
	ds_read2_b32 v[234:235], v28 offset0:130 offset1:195
	ds_read2_b32 v[236:237], v29 offset0:4 offset1:69
	ds_read2_b32 v[238:239], v29 offset0:134 offset1:199
	ds_read2_b32 v[240:241], v30 offset0:0 offset1:65
	ds_read2_b32 v[242:243], v30 offset0:130 offset1:195
	ds_read2_b32 v[244:245], v31 offset0:4 offset1:69
	ds_read2_b32 v[246:247], v31 offset0:134 offset1:199
	s_waitcnt lgkmcnt(0)
	v_cvt_pk_bf16_f32 v248, v232, v233
	v_cvt_pk_bf16_f32 v249, v234, v235
	v_cvt_pk_bf16_f32 v250, v236, v237
	v_cvt_pk_bf16_f32 v251, v238, v239
	v_cvt_pk_bf16_f32 v252, v240, v241
	v_cvt_pk_bf16_f32 v253, v242, v243
	v_cvt_pk_bf16_f32 v254, v244, v245
	v_cvt_pk_bf16_f32 v255, v246, v247
	global_store_dwordx4 v39, v[248:251], s[20:21]
	global_store_dwordx4 v39, v[252:255], s[20:21] offset:64
	v_add_u32_e32 v39, s53, v39
	s_waitcnt vmcnt(26)
	v_add_u32_e32 v40, s3, v37
	v_add_u32_e32 v40, 64, v40
	v_cmp_gt_u32_e32 vcc, s2, v40
	s_nop 1
	v_cndmask_b32_e32 v64, 0, v64, vcc
	v_cndmask_b32_e32 v65, 0, v65, vcc
	v_cndmask_b32_e32 v66, 0, v66, vcc
	v_cndmask_b32_e32 v67, 0, v67, vcc
	v_cndmask_b32_e32 v68, 0, v68, vcc
	v_cndmask_b32_e32 v69, 0, v69, vcc
	v_cndmask_b32_e32 v70, 0, v70, vcc
	v_cndmask_b32_e32 v71, 0, v71, vcc
	v_cndmask_b32_e32 v72, 0, v72, vcc
	v_cndmask_b32_e32 v73, 0, v73, vcc
	v_cndmask_b32_e32 v74, 0, v74, vcc
	v_cndmask_b32_e32 v75, 0, v75, vcc
	v_cndmask_b32_e32 v76, 0, v76, vcc
	v_cndmask_b32_e32 v77, 0, v77, vcc
	v_cndmask_b32_e32 v78, 0, v78, vcc
	v_cndmask_b32_e32 v79, 0, v79, vcc
	ds_write2_b32 v24, v64, v65 offset1:1
	ds_write2_b32 v24, v66, v67 offset0:2 offset1:3
	ds_write2_b32 v25, v68, v69 offset1:1
	ds_write2_b32 v25, v70, v71 offset0:2 offset1:3
	ds_write2_b32 v26, v72, v73 offset1:1
	ds_write2_b32 v26, v74, v75 offset0:2 offset1:3
	ds_write2_b32 v27, v76, v77 offset1:1
	ds_write2_b32 v27, v78, v79 offset0:2 offset1:3
	s_waitcnt lgkmcnt(0)
	s_barrier
	ds_read2_b32 v[232:233], v32 offset0:0 offset1:65
	ds_read2_b32 v[234:235], v32 offset0:130 offset1:195
	ds_read2_b32 v[236:237], v33 offset0:4 offset1:69
	ds_read2_b32 v[238:239], v33 offset0:134 offset1:199
	ds_read2_b32 v[240:241], v34 offset0:0 offset1:65
	ds_read2_b32 v[242:243], v34 offset0:130 offset1:195
	ds_read2_b32 v[244:245], v35 offset0:4 offset1:69
	ds_read2_b32 v[246:247], v35 offset0:134 offset1:199
	s_waitcnt lgkmcnt(0)
	v_cvt_pk_bf16_f32 v248, v232, v233
	v_cvt_pk_bf16_f32 v249, v234, v235
	v_cvt_pk_bf16_f32 v250, v236, v237
	v_cvt_pk_bf16_f32 v251, v238, v239
	v_cvt_pk_bf16_f32 v252, v240, v241
	v_cvt_pk_bf16_f32 v253, v242, v243
	v_cvt_pk_bf16_f32 v254, v244, v245
	v_cvt_pk_bf16_f32 v255, v246, v247
	global_store_dwordx4 v39, v[248:251], s[20:21]
	global_store_dwordx4 v39, v[252:255], s[20:21] offset:64
	v_add_u32_e32 v39, s53, v39
	s_waitcnt vmcnt(24)
	v_add_u32_e32 v40, s3, v37
	v_add_u32_e32 v40, 128, v40
	v_cmp_gt_u32_e32 vcc, s2, v40
	s_nop 1
	v_cndmask_b32_e32 v80, 0, v80, vcc
	v_cndmask_b32_e32 v81, 0, v81, vcc
	v_cndmask_b32_e32 v82, 0, v82, vcc
	v_cndmask_b32_e32 v83, 0, v83, vcc
	v_cndmask_b32_e32 v84, 0, v84, vcc
	v_cndmask_b32_e32 v85, 0, v85, vcc
	v_cndmask_b32_e32 v86, 0, v86, vcc
	v_cndmask_b32_e32 v87, 0, v87, vcc
	v_cndmask_b32_e32 v88, 0, v88, vcc
	v_cndmask_b32_e32 v89, 0, v89, vcc
	v_cndmask_b32_e32 v90, 0, v90, vcc
	v_cndmask_b32_e32 v91, 0, v91, vcc
	v_cndmask_b32_e32 v92, 0, v92, vcc
	v_cndmask_b32_e32 v93, 0, v93, vcc
	v_cndmask_b32_e32 v94, 0, v94, vcc
	v_cndmask_b32_e32 v95, 0, v95, vcc
	ds_write2_b32 v20, v80, v81 offset1:1
	ds_write2_b32 v20, v82, v83 offset0:2 offset1:3
	ds_write2_b32 v21, v84, v85 offset1:1
	ds_write2_b32 v21, v86, v87 offset0:2 offset1:3
	ds_write2_b32 v22, v88, v89 offset1:1
	ds_write2_b32 v22, v90, v91 offset0:2 offset1:3
	ds_write2_b32 v23, v92, v93 offset1:1
	ds_write2_b32 v23, v94, v95 offset0:2 offset1:3
	s_waitcnt lgkmcnt(0)
	s_barrier
	ds_read2_b32 v[232:233], v28 offset0:0 offset1:65
	ds_read2_b32 v[234:235], v28 offset0:130 offset1:195
	ds_read2_b32 v[236:237], v29 offset0:4 offset1:69
	ds_read2_b32 v[238:239], v29 offset0:134 offset1:199
	ds_read2_b32 v[240:241], v30 offset0:0 offset1:65
	ds_read2_b32 v[242:243], v30 offset0:130 offset1:195
	ds_read2_b32 v[244:245], v31 offset0:4 offset1:69
	ds_read2_b32 v[246:247], v31 offset0:134 offset1:199
	s_waitcnt lgkmcnt(0)
	v_cvt_pk_bf16_f32 v248, v232, v233
	v_cvt_pk_bf16_f32 v249, v234, v235
	v_cvt_pk_bf16_f32 v250, v236, v237
	v_cvt_pk_bf16_f32 v251, v238, v239
	v_cvt_pk_bf16_f32 v252, v240, v241
	v_cvt_pk_bf16_f32 v253, v242, v243
	v_cvt_pk_bf16_f32 v254, v244, v245
	v_cvt_pk_bf16_f32 v255, v246, v247
	global_store_dwordx4 v39, v[248:251], s[20:21]
	global_store_dwordx4 v39, v[252:255], s[20:21] offset:64
	v_add_u32_e32 v39, s53, v39
	s_waitcnt vmcnt(22)
	v_add_u32_e32 v40, s3, v37
	v_add_u32_e32 v40, 192, v40
	v_cmp_gt_u32_e32 vcc, s2, v40
	s_nop 1
	v_cndmask_b32_e32 v96, 0, v96, vcc
	v_cndmask_b32_e32 v97, 0, v97, vcc
	v_cndmask_b32_e32 v98, 0, v98, vcc
	v_cndmask_b32_e32 v99, 0, v99, vcc
	v_cndmask_b32_e32 v100, 0, v100, vcc
	v_cndmask_b32_e32 v101, 0, v101, vcc
	v_cndmask_b32_e32 v102, 0, v102, vcc
	v_cndmask_b32_e32 v103, 0, v103, vcc
	v_cndmask_b32_e32 v104, 0, v104, vcc
	v_cndmask_b32_e32 v105, 0, v105, vcc
	v_cndmask_b32_e32 v106, 0, v106, vcc
	v_cndmask_b32_e32 v107, 0, v107, vcc
	v_cndmask_b32_e32 v108, 0, v108, vcc
	v_cndmask_b32_e32 v109, 0, v109, vcc
	v_cndmask_b32_e32 v110, 0, v110, vcc
	v_cndmask_b32_e32 v111, 0, v111, vcc
	ds_write2_b32 v24, v96, v97 offset1:1
	ds_write2_b32 v24, v98, v99 offset0:2 offset1:3
	ds_write2_b32 v25, v100, v101 offset1:1
	ds_write2_b32 v25, v102, v103 offset0:2 offset1:3
	ds_write2_b32 v26, v104, v105 offset1:1
	ds_write2_b32 v26, v106, v107 offset0:2 offset1:3
	ds_write2_b32 v27, v108, v109 offset1:1
	ds_write2_b32 v27, v110, v111 offset0:2 offset1:3
	s_waitcnt lgkmcnt(0)
	s_barrier
	ds_read2_b32 v[232:233], v32 offset0:0 offset1:65
	ds_read2_b32 v[234:235], v32 offset0:130 offset1:195
	ds_read2_b32 v[236:237], v33 offset0:4 offset1:69
	ds_read2_b32 v[238:239], v33 offset0:134 offset1:199
	ds_read2_b32 v[240:241], v34 offset0:0 offset1:65
	ds_read2_b32 v[242:243], v34 offset0:130 offset1:195
	ds_read2_b32 v[244:245], v35 offset0:4 offset1:69
	ds_read2_b32 v[246:247], v35 offset0:134 offset1:199
	s_waitcnt lgkmcnt(0)
	v_cvt_pk_bf16_f32 v248, v232, v233
	v_cvt_pk_bf16_f32 v249, v234, v235
	v_cvt_pk_bf16_f32 v250, v236, v237
	v_cvt_pk_bf16_f32 v251, v238, v239
	v_cvt_pk_bf16_f32 v252, v240, v241
	v_cvt_pk_bf16_f32 v253, v242, v243
	v_cvt_pk_bf16_f32 v254, v244, v245
	v_cvt_pk_bf16_f32 v255, v246, v247
	global_store_dwordx4 v39, v[248:251], s[20:21]
	global_store_dwordx4 v39, v[252:255], s[20:21] offset:64
	v_add_u32_e32 v39, s53, v39
	s_waitcnt vmcnt(20)
	v_add_u32_e32 v40, s3, v37
	v_add_u32_e32 v40, 256, v40
	v_cmp_gt_u32_e32 vcc, s2, v40
	s_nop 1
	v_cndmask_b32_e32 v168, 0, v168, vcc
	v_cndmask_b32_e32 v169, 0, v169, vcc
	v_cndmask_b32_e32 v170, 0, v170, vcc
	v_cndmask_b32_e32 v171, 0, v171, vcc
	v_cndmask_b32_e32 v172, 0, v172, vcc
	v_cndmask_b32_e32 v173, 0, v173, vcc
	v_cndmask_b32_e32 v174, 0, v174, vcc
	v_cndmask_b32_e32 v175, 0, v175, vcc
	v_cndmask_b32_e32 v176, 0, v176, vcc
	v_cndmask_b32_e32 v177, 0, v177, vcc
	v_cndmask_b32_e32 v178, 0, v178, vcc
	v_cndmask_b32_e32 v179, 0, v179, vcc
	v_cndmask_b32_e32 v180, 0, v180, vcc
	v_cndmask_b32_e32 v181, 0, v181, vcc
	v_cndmask_b32_e32 v182, 0, v182, vcc
	v_cndmask_b32_e32 v183, 0, v183, vcc
	ds_write2_b32 v20, v168, v169 offset1:1
	ds_write2_b32 v20, v170, v171 offset0:2 offset1:3
	ds_write2_b32 v21, v172, v173 offset1:1
	ds_write2_b32 v21, v174, v175 offset0:2 offset1:3
	ds_write2_b32 v22, v176, v177 offset1:1
	ds_write2_b32 v22, v178, v179 offset0:2 offset1:3
	ds_write2_b32 v23, v180, v181 offset1:1
	ds_write2_b32 v23, v182, v183 offset0:2 offset1:3
	s_waitcnt lgkmcnt(0)
	s_barrier
	ds_read2_b32 v[232:233], v28 offset0:0 offset1:65
	ds_read2_b32 v[234:235], v28 offset0:130 offset1:195
	ds_read2_b32 v[236:237], v29 offset0:4 offset1:69
	ds_read2_b32 v[238:239], v29 offset0:134 offset1:199
	ds_read2_b32 v[240:241], v30 offset0:0 offset1:65
	ds_read2_b32 v[242:243], v30 offset0:130 offset1:195
	ds_read2_b32 v[244:245], v31 offset0:4 offset1:69
	ds_read2_b32 v[246:247], v31 offset0:134 offset1:199
	s_waitcnt lgkmcnt(0)
	v_cvt_pk_bf16_f32 v248, v232, v233
	v_cvt_pk_bf16_f32 v249, v234, v235
	v_cvt_pk_bf16_f32 v250, v236, v237
	v_cvt_pk_bf16_f32 v251, v238, v239
	v_cvt_pk_bf16_f32 v252, v240, v241
	v_cvt_pk_bf16_f32 v253, v242, v243
	v_cvt_pk_bf16_f32 v254, v244, v245
	v_cvt_pk_bf16_f32 v255, v246, v247
	global_store_dwordx4 v39, v[248:251], s[20:21]
	global_store_dwordx4 v39, v[252:255], s[20:21] offset:64
	v_add_u32_e32 v39, s53, v39
	s_waitcnt vmcnt(18)
	v_add_u32_e32 v40, s3, v37
	v_add_u32_e32 v40, 320, v40
	v_cmp_gt_u32_e32 vcc, s2, v40
	s_nop 1
	v_cndmask_b32_e32 v184, 0, v184, vcc
	v_cndmask_b32_e32 v185, 0, v185, vcc
	v_cndmask_b32_e32 v186, 0, v186, vcc
	v_cndmask_b32_e32 v187, 0, v187, vcc
	v_cndmask_b32_e32 v188, 0, v188, vcc
	v_cndmask_b32_e32 v189, 0, v189, vcc
	v_cndmask_b32_e32 v190, 0, v190, vcc
	v_cndmask_b32_e32 v191, 0, v191, vcc
	v_cndmask_b32_e32 v192, 0, v192, vcc
	v_cndmask_b32_e32 v193, 0, v193, vcc
	v_cndmask_b32_e32 v194, 0, v194, vcc
	v_cndmask_b32_e32 v195, 0, v195, vcc
	v_cndmask_b32_e32 v196, 0, v196, vcc
	v_cndmask_b32_e32 v197, 0, v197, vcc
	v_cndmask_b32_e32 v198, 0, v198, vcc
	v_cndmask_b32_e32 v199, 0, v199, vcc
	ds_write2_b32 v24, v184, v185 offset1:1
	ds_write2_b32 v24, v186, v187 offset0:2 offset1:3
	ds_write2_b32 v25, v188, v189 offset1:1
	ds_write2_b32 v25, v190, v191 offset0:2 offset1:3
	ds_write2_b32 v26, v192, v193 offset1:1
	ds_write2_b32 v26, v194, v195 offset0:2 offset1:3
	ds_write2_b32 v27, v196, v197 offset1:1
	ds_write2_b32 v27, v198, v199 offset0:2 offset1:3
	s_waitcnt lgkmcnt(0)
	s_barrier
	ds_read2_b32 v[232:233], v32 offset0:0 offset1:65
	ds_read2_b32 v[234:235], v32 offset0:130 offset1:195
	ds_read2_b32 v[236:237], v33 offset0:4 offset1:69
	ds_read2_b32 v[238:239], v33 offset0:134 offset1:199
	ds_read2_b32 v[240:241], v34 offset0:0 offset1:65
	ds_read2_b32 v[242:243], v34 offset0:130 offset1:195
	ds_read2_b32 v[244:245], v35 offset0:4 offset1:69
	ds_read2_b32 v[246:247], v35 offset0:134 offset1:199
	s_waitcnt lgkmcnt(0)
	v_cvt_pk_bf16_f32 v248, v232, v233
	v_cvt_pk_bf16_f32 v249, v234, v235
	v_cvt_pk_bf16_f32 v250, v236, v237
	v_cvt_pk_bf16_f32 v251, v238, v239
	v_cvt_pk_bf16_f32 v252, v240, v241
	v_cvt_pk_bf16_f32 v253, v242, v243
	v_cvt_pk_bf16_f32 v254, v244, v245
	v_cvt_pk_bf16_f32 v255, v246, v247
	global_store_dwordx4 v39, v[248:251], s[20:21]
	global_store_dwordx4 v39, v[252:255], s[20:21] offset:64
	v_add_u32_e32 v39, s53, v39
	s_waitcnt vmcnt(16)
	v_add_u32_e32 v40, s3, v37
	v_add_u32_e32 v40, 384, v40
	v_cmp_gt_u32_e32 vcc, s2, v40
	s_nop 1
	v_cndmask_b32_e32 v200, 0, v200, vcc
	v_cndmask_b32_e32 v201, 0, v201, vcc
	v_cndmask_b32_e32 v202, 0, v202, vcc
	v_cndmask_b32_e32 v203, 0, v203, vcc
	v_cndmask_b32_e32 v204, 0, v204, vcc
	v_cndmask_b32_e32 v205, 0, v205, vcc
	v_cndmask_b32_e32 v206, 0, v206, vcc
	v_cndmask_b32_e32 v207, 0, v207, vcc
	v_cndmask_b32_e32 v208, 0, v208, vcc
	v_cndmask_b32_e32 v209, 0, v209, vcc
	v_cndmask_b32_e32 v210, 0, v210, vcc
	v_cndmask_b32_e32 v211, 0, v211, vcc
	v_cndmask_b32_e32 v212, 0, v212, vcc
	v_cndmask_b32_e32 v213, 0, v213, vcc
	v_cndmask_b32_e32 v214, 0, v214, vcc
	v_cndmask_b32_e32 v215, 0, v215, vcc
	ds_write2_b32 v20, v200, v201 offset1:1
	ds_write2_b32 v20, v202, v203 offset0:2 offset1:3
	ds_write2_b32 v21, v204, v205 offset1:1
	ds_write2_b32 v21, v206, v207 offset0:2 offset1:3
	ds_write2_b32 v22, v208, v209 offset1:1
	ds_write2_b32 v22, v210, v211 offset0:2 offset1:3
	ds_write2_b32 v23, v212, v213 offset1:1
	ds_write2_b32 v23, v214, v215 offset0:2 offset1:3
	s_waitcnt lgkmcnt(0)
	s_barrier
	ds_read2_b32 v[232:233], v28 offset0:0 offset1:65
	ds_read2_b32 v[234:235], v28 offset0:130 offset1:195
	ds_read2_b32 v[236:237], v29 offset0:4 offset1:69
	ds_read2_b32 v[238:239], v29 offset0:134 offset1:199
	ds_read2_b32 v[240:241], v30 offset0:0 offset1:65
	ds_read2_b32 v[242:243], v30 offset0:130 offset1:195
	ds_read2_b32 v[244:245], v31 offset0:4 offset1:69
	ds_read2_b32 v[246:247], v31 offset0:134 offset1:199
	s_waitcnt lgkmcnt(0)
	v_cvt_pk_bf16_f32 v248, v232, v233
	v_cvt_pk_bf16_f32 v249, v234, v235
	v_cvt_pk_bf16_f32 v250, v236, v237
	v_cvt_pk_bf16_f32 v251, v238, v239
	v_cvt_pk_bf16_f32 v252, v240, v241
	v_cvt_pk_bf16_f32 v253, v242, v243
	v_cvt_pk_bf16_f32 v254, v244, v245
	v_cvt_pk_bf16_f32 v255, v246, v247
	global_store_dwordx4 v39, v[248:251], s[20:21]
	global_store_dwordx4 v39, v[252:255], s[20:21] offset:64
	v_add_u32_e32 v39, s53, v39
	s_waitcnt vmcnt(14)
	v_add_u32_e32 v40, s3, v37
	v_add_u32_e32 v40, 448, v40
	v_cmp_gt_u32_e32 vcc, s2, v40
	s_nop 1
	v_cndmask_b32_e32 v216, 0, v216, vcc
	v_cndmask_b32_e32 v217, 0, v217, vcc
	v_cndmask_b32_e32 v218, 0, v218, vcc
	v_cndmask_b32_e32 v219, 0, v219, vcc
	v_cndmask_b32_e32 v220, 0, v220, vcc
	v_cndmask_b32_e32 v221, 0, v221, vcc
	v_cndmask_b32_e32 v222, 0, v222, vcc
	v_cndmask_b32_e32 v223, 0, v223, vcc
	v_cndmask_b32_e32 v224, 0, v224, vcc
	v_cndmask_b32_e32 v225, 0, v225, vcc
	v_cndmask_b32_e32 v226, 0, v226, vcc
	v_cndmask_b32_e32 v227, 0, v227, vcc
	v_cndmask_b32_e32 v228, 0, v228, vcc
	v_cndmask_b32_e32 v229, 0, v229, vcc
	v_cndmask_b32_e32 v230, 0, v230, vcc
	v_cndmask_b32_e32 v231, 0, v231, vcc
	ds_write2_b32 v24, v216, v217 offset1:1
	ds_write2_b32 v24, v218, v219 offset0:2 offset1:3
	ds_write2_b32 v25, v220, v221 offset1:1
	ds_write2_b32 v25, v222, v223 offset0:2 offset1:3
	ds_write2_b32 v26, v224, v225 offset1:1
	ds_write2_b32 v26, v226, v227 offset0:2 offset1:3
	ds_write2_b32 v27, v228, v229 offset1:1
	ds_write2_b32 v27, v230, v231 offset0:2 offset1:3
	s_waitcnt lgkmcnt(0)
	s_barrier
	ds_read2_b32 v[232:233], v32 offset0:0 offset1:65
	ds_read2_b32 v[234:235], v32 offset0:130 offset1:195
	ds_read2_b32 v[236:237], v33 offset0:4 offset1:69
	ds_read2_b32 v[238:239], v33 offset0:134 offset1:199
	ds_read2_b32 v[240:241], v34 offset0:0 offset1:65
	ds_read2_b32 v[242:243], v34 offset0:130 offset1:195
	ds_read2_b32 v[244:245], v35 offset0:4 offset1:69
	ds_read2_b32 v[246:247], v35 offset0:134 offset1:199
	s_waitcnt lgkmcnt(0)
	v_cvt_pk_bf16_f32 v248, v232, v233
	v_cvt_pk_bf16_f32 v249, v234, v235
	v_cvt_pk_bf16_f32 v250, v236, v237
	v_cvt_pk_bf16_f32 v251, v238, v239
	v_cvt_pk_bf16_f32 v252, v240, v241
	v_cvt_pk_bf16_f32 v253, v242, v243
	v_cvt_pk_bf16_f32 v254, v244, v245
	v_cvt_pk_bf16_f32 v255, v246, v247
	global_store_dwordx4 v39, v[248:251], s[20:21]
	global_store_dwordx4 v39, v[252:255], s[20:21] offset:64
	s_waitcnt lgkmcnt(0)
	s_barrier
	s_mov_b64 s[20:21], 0
	s_branch .LBB0_634

.Lgro8_rm_done:
	s_mul_i32 s4, s34, 0x1b000
	s_add_u32 s6, s4, 0x5000
	s_add_u32 s7, s4, 0x6000

.LBB0_1112:
	v_readlane_b32 s10, v164, 0
	v_readlane_b32 s11, v162, 14
	v_lshrrev_b32_e32 v80, 6, v128
	v_and_b32_e32 v81, 63, v128
	v_readlane_b32 s16, v163, 13
	v_readlane_b32 s17, v163, 14
	v_readlane_b32 s18, v163, 15
	v_readlane_b32 s19, v163, 16
	v_readfirstlane_b32 s12, v80
	v_lshlrev_b32_e32 v82, 4, v81
	v_lshlrev_b32_e32 v83, 5, v81
	s_lshl_b32 s13, s10, 2
	s_add_u32 s13, s13, s12
	s_lshl_b32 s14, s11, 2
	s_mul_i32 s36, s14, 5
	s_cmp_lg_u32 s11, 0x200
	s_cbranch_scc1 .Lgro11_rm_done
	s_and_b32 s4, s10, 7
	s_lshl_b32 s4, s4, 3
	s_bfe_u32 s32, s10, 0x30003
	s_or_b32 s4, s4, s32
	s_mul_i32 s4, s4, 0xa0
	s_lshr_b32 s32, s10, 6
	s_mul_i32 s32, s32, 20
	s_add_u32 s4, s4, s32
	s_mul_i32 s32, s12, 5
	s_add_u32 s13, s4, s32
	s_mov_b32 s14, 1
	s_mov_b32 s36, 0x2800
.Lgro11_rm_done:
	s_mul_i32 s4, s34, 0x1b000
	s_add_u32 s6, s4, 0x8000
	s_mov_b32 s7, 0x1b000
	v_readlane_b32 s8, v164, 61
	v_readlane_b32 s9, v164, 62

.Lgro11_r4_done:
.Lgro11_bend:
	s_add_u32 s13, s13, s36
	s_cmp_lt_u32 s13, 0x2800
	s_cbranch_scc1 .Lgro11_batch

.LBB0_1123:
	s_waitcnt vmcnt(0) lgkmcnt(0)
	ds_read_b32 v2, v117 offset:53248
	ds_read_b32 v3, v117 offset:53252
	v_readlane_b32 s4, v163, 62
	v_readlane_b32 s5, v163, 63
	v_readlane_b32 s36, v162, 60
	s_nop 1
	s_add_u32 s36, s36, 1
	s_nop 2
	v_writelane_b32 v162, s36, 60
	global_atomic_add v0, v117, v129, s[4:5] offset:64 sc0
	s_waitcnt lgkmcnt(0)
	v_lshrrev_b32_e32 v4, 1, v2
	v_mul_lo_u32 v2, v2, s36
	v_mul_lo_u32 v3, v3, s36
	v_readlane_b32 s4, v162, 2
	v_readlane_b32 s5, v162, 3
	s_waitcnt vmcnt(0)
	v_add_u32_e32 v0, 1, v0
	s_nop 0
	v_cmp_eq_u32_e32 vcc, v0, v2
	s_nop 3
	s_cbranch_vccz .Lxb11_poll
	v_readlane_b32 s20, v162, 62
	s_nop 1
	s_cmp_eq_u32 s20, 1
	s_cbranch_scc1 .Lxb11_nowb
	buffer_wbl2 sc1
	s_waitcnt vmcnt(0)
